# S5 stage-3: interleaved re/im state layout in LDS (one ds_write_b32 per step), batched C-coefficient loads
# speedup vs baseline: 1.0048x; 1.0048x over previous
.LBB0_1518:
	s_cmp_lt_i32 s94, 9
	s_cselect_b64 s[2:3], -1, 0
	s_and_b64 s[0:1], s[2:3], s[0:1]
	s_andn2_b64 vcc, exec, s[0:1]
	s_cbranch_vccnz .LBB0_1563
	v_readlane_b32 s2, v243, 60
	s_cmpk_gt_i32 s2, 0x5fff
	v_readlane_b32 s3, v243, 61
	s_cbranch_scc1 .LBB0_1562
	v_readlane_b32 s4, v243, 48
	v_readlane_b32 s2, v243, 39
	v_and_b32_e32 v176, 48, v172
	v_mov_b32_e32 v177, 0
	v_readlane_b32 s5, v243, 49
	s_mulk_i32 s2, 0x3900
	s_add_i32 s2, s2, 0
	v_lshl_add_u64 v[180:181], s[4:5], 0, v[176:177]
	v_readlane_b32 s4, v242, 4
	v_lshlrev_b32_e32 v182, 3, v172
	v_mov_b32_e32 v183, v177
	v_readlane_b32 s5, v242, 5
	s_waitcnt vmcnt(0)
	v_and_b32_e32 v2, 48, v174
	v_and_b32_e32 v173, 15, v174
	v_lshrrev_b32_e32 v0, 4, v172
	v_lshl_add_u64 v[184:185], s[4:5], 0, v[182:183]
	v_add_u32_e32 v3, s2, v2
	s_movk_i32 s4, 0x50
	v_mov_b32_e32 v4, s2
	s_movk_i32 s2, 0x110
	v_or_b32_e32 v7, 48, v172
	v_or_b32_e32 v8, 0x70, v172
	v_lshlrev_b32_e32 v9, 4, v172
	v_lshl_add_u64 v[178:179], s[60:61], 0, v[176:177]
	s_waitcnt lgkmcnt(0)
	v_lshlrev_b32_e32 v1, 6, v173
	v_mad_u32_u24 v175, v172, s4, v4
	v_mad_u32_u24 v4, v173, s2, v4
	v_lshlrev_b32_e32 v5, 4, v173
	v_mul_u32_u24_e32 v6, 0x50, v173
	v_mul_u32_u24_e32 v7, 0x50, v7
	v_mul_u32_u24_e32 v8, 0x50, v8
	s_movk_i32 s2, 0xffb2
	v_or_b32_e32 v10, 0x100, v9
	v_or_b32_e32 v11, 0x300, v9
	v_or_b32_e32 v12, 0x500, v9
	v_or_b32_e32 v9, 0x700, v9
	v_lshlrev_b32_e32 v176, 4, v0
	v_readlane_b32 s4, v243, 60
	s_mov_b32 s3, 0
	v_cmp_gt_u32_e32 vcc, 32, v172
	v_mad_i32_i24 v183, v172, s2, v175
	v_lshl_add_u32 v205, v172, 1, v183
	v_lshlrev_b32_e32 v194, 2, v0
	v_lshl_add_u64 v[186:187], s[42:43], 0, v[176:177]
	v_lshl_add_u64 v[188:189], s[44:45], 0, v[176:177]
	v_lshlrev_b32_e32 v195, 1, v5
	v_lshlrev_b32_e32 v196, 1, v10
	v_lshlrev_b32_e32 v197, 1, v11
	v_lshlrev_b32_e32 v198, 1, v12
	v_lshlrev_b32_e32 v199, 1, v9
	v_lshlrev_b32_e32 v200, 2, v1
	v_add_u32_e32 v201, v3, v6
	v_add_u32_e32 v202, v3, v7
	v_add_u32_e32 v203, v3, v8
	v_add_u32_e32 v204, v4, v2
	s_mov_b32 s6, s4
	v_readlane_b32 s5, v243, 61
	s_branch .LBB0_1522
.LBB0_1521:
	s_or_b64 exec, exec, s[4:5]
	v_lshl_or_b32 v176, s10, 12, v200
	v_lshl_add_u64 v[238:239], v[186:187], 0, v[176:177]
	v_lshl_add_u64 v[112:113], v[188:189], 0, v[176:177]
	global_load_dwordx4 v[214:217], v[238:239], off
	global_load_dwordx4 v[218:221], v[112:113], off
	global_load_dwordx4 v[222:225], v[238:239], off offset:64
	global_load_dwordx4 v[226:229], v[112:113], off offset:64
	global_load_dwordx4 v[230:233], v[238:239], off offset:128
	global_load_dwordx4 v[234:237], v[112:113], off offset:128
	global_load_dwordx4 v[76:79], v[238:239], off offset:192
	global_load_dwordx4 v[116:119], v[112:113], off offset:192
	s_waitcnt vmcnt(6)
	v_xor_b32_e32 v218, 0x80000000, v218
	v_xor_b32_e32 v219, 0x80000000, v219
	v_xor_b32_e32 v220, 0x80000000, v220
	v_xor_b32_e32 v221, 0x80000000, v221
	v_cvt_pk_bf16_f32 v60, v214, v218
	v_cvt_pk_bf16_f32 v61, v215, v219
	v_cvt_pk_bf16_f32 v62, v216, v220
	v_cvt_pk_bf16_f32 v63, v217, v221
	s_waitcnt vmcnt(4)
	v_xor_b32_e32 v226, 0x80000000, v226
	v_xor_b32_e32 v227, 0x80000000, v227
	v_xor_b32_e32 v228, 0x80000000, v228
	v_xor_b32_e32 v229, 0x80000000, v229
	v_cvt_pk_bf16_f32 v56, v222, v226
	v_cvt_pk_bf16_f32 v57, v223, v227
	v_cvt_pk_bf16_f32 v58, v224, v228
	v_cvt_pk_bf16_f32 v59, v225, v229
	s_waitcnt vmcnt(2)
	v_xor_b32_e32 v234, 0x80000000, v234
	v_xor_b32_e32 v235, 0x80000000, v235
	v_xor_b32_e32 v236, 0x80000000, v236
	v_xor_b32_e32 v237, 0x80000000, v237
	v_cvt_pk_bf16_f32 v72, v230, v234
	v_cvt_pk_bf16_f32 v73, v231, v235
	v_cvt_pk_bf16_f32 v74, v232, v236
	v_cvt_pk_bf16_f32 v75, v233, v237
	s_waitcnt vmcnt(0)
	v_xor_b32_e32 v116, 0x80000000, v116
	v_xor_b32_e32 v117, 0x80000000, v117
	v_xor_b32_e32 v118, 0x80000000, v118
	v_xor_b32_e32 v119, 0x80000000, v119
	v_cvt_pk_bf16_f32 v76, v76, v116
	v_cvt_pk_bf16_f32 v77, v77, v117
	v_cvt_pk_bf16_f32 v78, v78, v118
	v_cvt_pk_bf16_f32 v79, v79, v119
	s_or_b32 s4, s9, 1
	s_ashr_i32 s5, s4, 31
	s_lshl_b64 s[4:5], s[4:5], 15
	v_lshl_add_u64 v[128:129], v[192:193], 0, s[4:5]
	v_mfma_f32_16x16x32_bf16 v[80:83], v[12:15], v[32:35], 0
	s_add_i32 s6, s6, s28
	s_cmpk_gt_i32 s6, 0x5fff
	v_mfma_f32_16x16x32_bf16 v[84:87], v[12:15], v[36:39], 0
	global_load_dwordx2 v[128:129], v[128:129], off
	v_mfma_f32_16x16x32_bf16 v[88:91], v[12:15], v[40:43], 0
	v_mfma_f32_16x16x32_bf16 v[92:95], v[12:15], v[44:47], 0
	v_mfma_f32_16x16x32_bf16 v[96:99], v[12:15], v[48:51], 0
	v_mfma_f32_16x16x32_bf16 v[100:103], v[12:15], v[52:55], 0
	v_mfma_f32_16x16x32_bf16 v[120:123], v[12:15], v[64:67], 0
	v_mfma_f32_16x16x32_bf16 v[124:127], v[12:15], v[68:71], 0
	ds_write_b128 v201, v[80:83]
	ds_write_b128 v201, v[84:87] offset:1280
	s_nop 0
	ds_write_b128 v201, v[88:91] offset:2560
	ds_write_b128 v202, v[92:95]
	ds_write_b128 v201, v[96:99] offset:5120
	ds_write_b128 v201, v[100:103] offset:6400
	ds_write_b128 v201, v[120:123] offset:7680
	ds_write_b128 v203, v[124:127]
	s_waitcnt lgkmcnt(0)
	ds_read_b128 v[12:15], v175 offset:48
	ds_read_b128 v[80:83], v175 offset:5168
	v_mfma_f32_16x16x32_bf16 v[132:135], v[8:11], v[32:35], 0
	s_waitcnt vmcnt(0) lgkmcnt(1)
	v_fma_f32 v15, -v169, v129, v15
	s_waitcnt lgkmcnt(0)
	v_fma_f32 v83, v169, v128, v83
	v_fmac_f32_e32 v15, v168, v128
	v_fmac_f32_e32 v83, v168, v129
	v_fma_f32 v14, -v169, v83, v14
	v_cvt_pk_bf16_f32 v84, v15, v83
	v_fmac_f32_e32 v14, v168, v15
	v_fma_f32 v15, v169, v15, v82
	ds_write_b32 v205, v84 offset:14320
	v_fmac_f32_e32 v15, v168, v83
	v_fma_f32 v13, -v169, v15, v13
	v_fma_f32 v81, v169, v14, v81
	v_fmac_f32_e32 v81, v168, v15
	v_cvt_pk_bf16_f32 v82, v14, v15
	v_fmac_f32_e32 v13, v168, v14
	v_fma_f32 v86, -v169, v81, v12
	ds_write_b32 v205, v82 offset:14048
	v_mfma_f32_16x16x32_bf16 v[136:139], v[8:11], v[36:39], 0
	v_cvt_pk_bf16_f32 v12, v13, v81
	v_fmac_f32_e32 v86, v168, v13
	v_fmac_f32_e32 v80, v169, v13
	ds_write_b32 v205, v12 offset:13776
	v_fmac_f32_e32 v80, v168, v81
	v_mfma_f32_16x16x32_bf16 v[140:143], v[8:11], v[40:43], 0
	v_cvt_pk_bf16_f32 v12, v86, v80
	ds_write_b32 v205, v12 offset:13504
	ds_read_b128 v[12:15], v175 offset:32
	ds_read_b128 v[82:85], v175 offset:5152
	v_mfma_f32_16x16x32_bf16 v[144:147], v[8:11], v[44:47], 0
	s_waitcnt lgkmcnt(1)
	v_fma_f32 v15, -v169, v80, v15
	s_waitcnt lgkmcnt(0)
	v_fma_f32 v81, v169, v86, v85
	v_fmac_f32_e32 v15, v168, v86
	v_fmac_f32_e32 v81, v168, v80
	v_fma_f32 v14, -v169, v81, v14
	v_cvt_pk_bf16_f32 v80, v15, v81
	v_fmac_f32_e32 v14, v168, v15
	v_fma_f32 v15, v169, v15, v84
	ds_write_b32 v205, v80 offset:13232
	v_fmac_f32_e32 v15, v168, v81
	v_fma_f32 v13, -v169, v15, v13
	v_fma_f32 v81, v169, v14, v83
	v_cvt_pk_bf16_f32 v80, v14, v15
	v_fmac_f32_e32 v81, v168, v15
	ds_write_b32 v205, v80 offset:12960
	v_fmac_f32_e32 v13, v168, v14
	v_fma_f32 v80, -v169, v81, v12
	v_mfma_f32_16x16x32_bf16 v[148:151], v[8:11], v[48:51], 0
	v_cvt_pk_bf16_f32 v12, v13, v81
	v_fmac_f32_e32 v80, v168, v13
	v_fmac_f32_e32 v82, v169, v13
	ds_write_b32 v205, v12 offset:12688
	v_fmac_f32_e32 v82, v168, v81
	v_mfma_f32_16x16x32_bf16 v[152:155], v[8:11], v[52:55], 0
	v_cvt_pk_bf16_f32 v12, v80, v82
	ds_write_b32 v205, v12 offset:12416
	ds_read_b128 v[12:15], v175 offset:16
	ds_read_b128 v[84:87], v175 offset:5136
	v_mfma_f32_16x16x32_bf16 v[156:159], v[8:11], v[64:67], 0
	s_waitcnt lgkmcnt(1)
	v_fma_f32 v15, -v169, v82, v15
	s_waitcnt lgkmcnt(0)
	v_fma_f32 v81, v169, v80, v87
	v_fmac_f32_e32 v15, v168, v80
	v_fmac_f32_e32 v81, v168, v82
	v_fma_f32 v14, -v169, v81, v14
	v_cvt_pk_bf16_f32 v80, v15, v81
	v_fmac_f32_e32 v14, v168, v15
	v_fma_f32 v15, v169, v15, v86
	ds_write_b32 v205, v80 offset:12144
	v_fmac_f32_e32 v15, v168, v81
	v_fma_f32 v13, -v169, v15, v13
	v_fma_f32 v81, v169, v14, v85
	v_cvt_pk_bf16_f32 v80, v14, v15
	v_fmac_f32_e32 v81, v168, v15
	ds_write_b32 v205, v80 offset:11872
	v_fmac_f32_e32 v13, v168, v14
	v_fma_f32 v80, -v169, v81, v12
	v_mfma_f32_16x16x32_bf16 v[160:163], v[8:11], v[68:71], 0
	v_cvt_pk_bf16_f32 v12, v13, v81
	v_fmac_f32_e32 v80, v168, v13
	v_fmac_f32_e32 v84, v169, v13
	ds_write_b32 v205, v12 offset:11600
	v_fmac_f32_e32 v84, v168, v81
	v_mfma_f32_16x16x32_bf16 v[104:107], v[4:7], v[32:35], 0
	v_cvt_pk_bf16_f32 v12, v80, v84
	ds_write_b32 v205, v12 offset:11328
	ds_read_b128 v[12:15], v175
	ds_read_b128 v[92:95], v175 offset:5120
	v_mfma_f32_16x16x32_bf16 v[108:111], v[4:7], v[36:39], 0
	s_waitcnt lgkmcnt(1)
	v_fma_f32 v15, -v169, v84, v15
	s_waitcnt lgkmcnt(0)
	v_fma_f32 v81, v169, v80, v95
	v_fmac_f32_e32 v15, v168, v80
	v_fmac_f32_e32 v81, v168, v84
	v_fma_f32 v14, -v169, v81, v14
	v_cvt_pk_bf16_f32 v80, v15, v81
	v_fmac_f32_e32 v14, v168, v15
	v_fma_f32 v15, v169, v15, v94
	ds_write_b32 v205, v80 offset:11056
	v_fmac_f32_e32 v15, v168, v81
	v_fma_f32 v13, -v169, v15, v13
	v_fma_f32 v81, v169, v14, v93
	v_fmac_f32_e32 v81, v168, v15
	v_cvt_pk_bf16_f32 v80, v14, v15
	v_fmac_f32_e32 v13, v168, v14
	v_fma_f32 v93, -v169, v81, v12
	ds_write_b32 v205, v80 offset:10784
	v_mfma_f32_16x16x32_bf16 v[112:115], v[4:7], v[40:43], 0
	v_cvt_pk_bf16_f32 v12, v13, v81
	v_fmac_f32_e32 v93, v168, v13
	v_fmac_f32_e32 v92, v169, v13
	ds_write_b32 v205, v12 offset:10512
	v_fmac_f32_e32 v92, v168, v81
	v_mfma_f32_16x16x32_bf16 v[116:119], v[4:7], v[44:47], 0
	v_cvt_pk_bf16_f32 v12, v93, v92
	ds_write_b32 v205, v12 offset:10240
	s_waitcnt lgkmcnt(0)
	ds_read_b128 v[88:91], v204 offset:10240
	ds_read_b128 v[84:87], v204 offset:10304
	ds_read_b128 v[80:83], v204 offset:10368
	ds_read_b128 v[12:15], v204 offset:10432
	s_waitcnt lgkmcnt(0)
	ds_write_b128 v201, v[132:135]
	ds_write_b128 v201, v[136:139] offset:1280
	ds_write_b128 v201, v[140:143] offset:2560
	ds_write_b128 v202, v[144:147]
	ds_write_b128 v201, v[148:151] offset:5120
	ds_write_b128 v201, v[152:155] offset:6400
	ds_write_b128 v201, v[156:159] offset:7680
	ds_write_b128 v203, v[160:163]
	s_waitcnt lgkmcnt(0)
	ds_read_b128 v[94:97], v175 offset:48
	ds_read_b128 v[8:11], v175 offset:5168
	v_mfma_f32_16x16x32_bf16 v[120:123], v[4:7], v[48:51], 0
	s_waitcnt lgkmcnt(1)
	v_fma_f32 v97, -v169, v92, v97
	s_waitcnt lgkmcnt(0)
	v_fma_f32 v11, v169, v93, v11
	v_fmac_f32_e32 v11, v168, v92
	v_fmac_f32_e32 v97, v168, v93
	v_fma_f32 v92, -v169, v11, v96
	v_mfma_f32_16x16x32_bf16 v[124:127], v[4:7], v[52:55], 0
	v_cvt_pk_bf16_f32 v93, v97, v11
	v_fmac_f32_e32 v92, v168, v97
	v_fma_f32 v10, v169, v97, v10
	ds_write_b32 v205, v93 offset:14320
	v_fmac_f32_e32 v10, v168, v11
	v_fma_f32 v93, -v169, v10, v95
	v_fma_f32 v9, v169, v92, v9
	v_fmac_f32_e32 v9, v168, v10
	v_cvt_pk_bf16_f32 v11, v92, v10
	v_fmac_f32_e32 v93, v168, v92
	v_fma_f32 v10, -v169, v9, v94
	ds_write_b32 v205, v11 offset:14048
	v_mfma_f32_16x16x32_bf16 v[128:131], v[4:7], v[64:67], 0
	v_cvt_pk_bf16_f32 v11, v93, v9
	v_fmac_f32_e32 v10, v168, v93
	v_fmac_f32_e32 v8, v169, v93
	ds_write_b32 v205, v11 offset:13776
	v_fmac_f32_e32 v8, v168, v9
	v_mfma_f32_16x16x32_bf16 v[164:167], v[4:7], v[68:71], 0
	v_cvt_pk_bf16_f32 v9, v10, v8
	ds_write_b32 v205, v9 offset:13504
	ds_read_b128 v[92:95], v175 offset:32
	ds_read_b128 v[96:99], v175 offset:5152
	v_mfma_f32_16x16x32_bf16 v[132:135], v[0:3], v[32:35], 0
	s_waitcnt lgkmcnt(1)
	v_fma_f32 v9, -v169, v8, v95
	s_waitcnt lgkmcnt(0)
	v_fma_f32 v11, v169, v10, v99
	v_fmac_f32_e32 v9, v168, v10
	v_fmac_f32_e32 v11, v168, v8
	v_fma_f32 v8, -v169, v11, v94
	v_cvt_pk_bf16_f32 v10, v9, v11
	v_fmac_f32_e32 v8, v168, v9
	v_fma_f32 v9, v169, v9, v98
	v_fmac_f32_e32 v9, v168, v11
	ds_write_b32 v205, v10 offset:13232
	v_fma_f32 v11, -v169, v9, v93
	v_fma_f32 v93, v169, v8, v97
	v_fmac_f32_e32 v93, v168, v9
	v_cvt_pk_bf16_f32 v10, v8, v9
	v_fmac_f32_e32 v11, v168, v8
	v_fma_f32 v97, -v169, v93, v92
	ds_write_b32 v205, v10 offset:12960
	v_mfma_f32_16x16x32_bf16 v[136:139], v[0:3], v[36:39], 0
	v_cvt_pk_bf16_f32 v8, v11, v93
	v_fmac_f32_e32 v97, v168, v11
	v_fmac_f32_e32 v96, v169, v11
	ds_write_b32 v205, v8 offset:12688
	v_fmac_f32_e32 v96, v168, v93
	v_mfma_f32_16x16x32_bf16 v[140:143], v[0:3], v[40:43], 0
	v_cvt_pk_bf16_f32 v8, v97, v96
	ds_write_b32 v205, v8 offset:12416
	ds_read_b128 v[8:11], v175 offset:16
	ds_read_b128 v[92:95], v175 offset:5136
	v_mfma_f32_16x16x32_bf16 v[148:151], v[0:3], v[44:47], 0
	s_waitcnt lgkmcnt(1)
	v_fma_f32 v11, -v169, v96, v11
	s_waitcnt lgkmcnt(0)
	v_fma_f32 v95, v169, v97, v95
	v_fmac_f32_e32 v11, v168, v97
	v_fmac_f32_e32 v95, v168, v96
	v_fma_f32 v10, -v169, v95, v10
	v_cvt_pk_bf16_f32 v96, v11, v95
	v_fmac_f32_e32 v10, v168, v11
	v_fma_f32 v11, v169, v11, v94
	ds_write_b32 v205, v96 offset:12144
	v_fmac_f32_e32 v11, v168, v95
	v_fma_f32 v9, -v169, v11, v9
	v_fma_f32 v93, v169, v10, v93
	v_cvt_pk_bf16_f32 v94, v10, v11
	v_fmac_f32_e32 v93, v168, v11
	ds_write_b32 v205, v94 offset:11872
	v_fmac_f32_e32 v9, v168, v10
	v_fma_f32 v94, -v169, v93, v8
	s_nop 0
	v_cvt_pk_bf16_f32 v8, v9, v93
	v_fmac_f32_e32 v94, v168, v9
	v_fmac_f32_e32 v92, v169, v9
	ds_write_b32 v205, v8 offset:11600
	v_fmac_f32_e32 v92, v168, v93
	s_nop 0
	v_cvt_pk_bf16_f32 v8, v94, v92
	ds_write_b32 v205, v8 offset:11328
	ds_read_b128 v[8:11], v175
	ds_read_b128 v[144:147], v175 offset:5120
	s_waitcnt lgkmcnt(1)
	v_fma_f32 v11, -v169, v92, v11
	s_waitcnt lgkmcnt(0)
	v_fma_f32 v93, v169, v94, v147
	v_fmac_f32_e32 v11, v168, v94
	v_fmac_f32_e32 v93, v168, v92
	v_fma_f32 v10, -v169, v93, v10
	v_cvt_pk_bf16_f32 v92, v11, v93
	v_fmac_f32_e32 v10, v168, v11
	v_fma_f32 v11, v169, v11, v146
	ds_write_b32 v205, v92 offset:11056
	v_fmac_f32_e32 v11, v168, v93
	v_fma_f32 v9, -v169, v11, v9
	v_fma_f32 v93, v169, v10, v145
	v_fmac_f32_e32 v93, v168, v11
	v_cvt_pk_bf16_f32 v92, v10, v11
	v_fmac_f32_e32 v9, v168, v10
	v_fma_f32 v145, -v169, v93, v8
	ds_write_b32 v205, v92 offset:10784
	s_nop 0
	v_cvt_pk_bf16_f32 v8, v9, v93
	v_fmac_f32_e32 v145, v168, v9
	v_fmac_f32_e32 v144, v169, v9
	ds_write_b32 v205, v8 offset:10512
	v_fmac_f32_e32 v144, v168, v93
	s_nop 0
	v_cvt_pk_bf16_f32 v8, v145, v144
	ds_write_b32 v205, v8 offset:10240
	s_waitcnt lgkmcnt(0)
	ds_read_b128 v[100:103], v204 offset:10240
	ds_read_b128 v[96:99], v204 offset:10304
	ds_read_b128 v[92:95], v204 offset:10368
	ds_read_b128 v[8:11], v204 offset:10432
	s_waitcnt lgkmcnt(0)
	ds_write_b128 v201, v[104:107]
	ds_write_b128 v201, v[108:111] offset:1280
	ds_write_b128 v201, v[112:115] offset:2560
	ds_write_b128 v202, v[116:119]
	ds_write_b128 v201, v[120:123] offset:5120
	ds_write_b128 v201, v[124:127] offset:6400
	ds_write_b128 v201, v[128:131] offset:7680
	ds_write_b128 v203, v[164:167]
	s_waitcnt lgkmcnt(0)
	ds_read_b128 v[4:7], v175 offset:48
	ds_read_b128 v[104:107], v175 offset:5168
	v_mfma_f32_16x16x32_bf16 v[116:119], v[0:3], v[48:51], 0
	s_waitcnt lgkmcnt(1)
	v_fma_f32 v7, -v169, v144, v7
	s_waitcnt lgkmcnt(0)
	v_fma_f32 v107, v169, v145, v107
	v_fmac_f32_e32 v7, v168, v145
	v_fmac_f32_e32 v107, v168, v144
	v_fma_f32 v6, -v169, v107, v6
	v_cvt_pk_bf16_f32 v108, v7, v107
	v_fmac_f32_e32 v6, v168, v7
	v_fma_f32 v7, v169, v7, v106
	ds_write_b32 v205, v108 offset:14320
	v_fmac_f32_e32 v7, v168, v107
	v_fma_f32 v5, -v169, v7, v5
	v_fma_f32 v105, v169, v6, v105
	v_fmac_f32_e32 v105, v168, v7
	v_cvt_pk_bf16_f32 v106, v6, v7
	v_fmac_f32_e32 v5, v168, v6
	v_fma_f32 v110, -v169, v105, v4
	ds_write_b32 v205, v106 offset:14048
	v_mfma_f32_16x16x32_bf16 v[120:123], v[0:3], v[52:55], 0
	v_cvt_pk_bf16_f32 v4, v5, v105
	v_fmac_f32_e32 v110, v168, v5
	v_fmac_f32_e32 v104, v169, v5
	ds_write_b32 v205, v4 offset:13776
	v_fmac_f32_e32 v104, v168, v105
	v_mfma_f32_16x16x32_bf16 v[124:127], v[0:3], v[64:67], 0
	v_cvt_pk_bf16_f32 v4, v110, v104
	ds_write_b32 v205, v4 offset:13504
	ds_read_b128 v[4:7], v175 offset:32
	ds_read_b128 v[106:109], v175 offset:5152
	v_mfma_f32_16x16x32_bf16 v[144:147], v[0:3], v[68:71], 0
	s_waitcnt lgkmcnt(1)
	v_fma_f32 v7, -v169, v104, v7
	s_waitcnt lgkmcnt(0)
	v_fma_f32 v105, v169, v110, v109
	v_fmac_f32_e32 v7, v168, v110
	v_fmac_f32_e32 v105, v168, v104
	v_fma_f32 v6, -v169, v105, v6
	v_cvt_pk_bf16_f32 v104, v7, v105
	v_fmac_f32_e32 v6, v168, v7
	v_fma_f32 v7, v169, v7, v108
	ds_write_b32 v205, v104 offset:13232
	v_fmac_f32_e32 v7, v168, v105
	v_fma_f32 v5, -v169, v7, v5
	v_fma_f32 v105, v169, v6, v107
	v_cvt_pk_bf16_f32 v104, v6, v7
	v_fmac_f32_e32 v105, v168, v7
	ds_write_b32 v205, v104 offset:12960
	v_fmac_f32_e32 v5, v168, v6
	v_fma_f32 v104, -v169, v105, v4
	s_nop 0
	v_cvt_pk_bf16_f32 v4, v5, v105
	v_fmac_f32_e32 v104, v168, v5
	v_fmac_f32_e32 v106, v169, v5
	ds_write_b32 v205, v4 offset:12688
	v_fmac_f32_e32 v106, v168, v105
	s_nop 0
	v_cvt_pk_bf16_f32 v4, v104, v106
	ds_write_b32 v205, v4 offset:12416
	ds_read_b128 v[4:7], v175 offset:16
	ds_read_b128 v[108:111], v175 offset:5136
	s_waitcnt lgkmcnt(1)
	v_fma_f32 v7, -v169, v106, v7
	s_waitcnt lgkmcnt(0)
	v_fma_f32 v105, v169, v104, v111
	v_fmac_f32_e32 v7, v168, v104
	v_fmac_f32_e32 v105, v168, v106
	v_fma_f32 v6, -v169, v105, v6
	v_cvt_pk_bf16_f32 v104, v7, v105
	v_fmac_f32_e32 v6, v168, v7
	v_fma_f32 v7, v169, v7, v110
	ds_write_b32 v205, v104 offset:12144
	v_fmac_f32_e32 v7, v168, v105
	v_fma_f32 v5, -v169, v7, v5
	v_fma_f32 v105, v169, v6, v109
	v_cvt_pk_bf16_f32 v104, v6, v7
	v_fmac_f32_e32 v105, v168, v7
	ds_write_b32 v205, v104 offset:11872
	v_fmac_f32_e32 v5, v168, v6
	v_fma_f32 v104, -v169, v105, v4
	s_nop 0
	v_cvt_pk_bf16_f32 v4, v5, v105
	v_fmac_f32_e32 v104, v168, v5
	v_fmac_f32_e32 v108, v169, v5
	ds_write_b32 v205, v4 offset:11600
	v_fmac_f32_e32 v108, v168, v105
	s_nop 0
	v_cvt_pk_bf16_f32 v4, v104, v108
	ds_write_b32 v205, v4 offset:11328
	ds_read_b128 v[4:7], v175
	ds_read_b128 v[128:131], v175 offset:5120
	s_waitcnt lgkmcnt(1)
	v_fma_f32 v7, -v169, v108, v7
	s_waitcnt lgkmcnt(0)
	v_fma_f32 v105, v169, v104, v131
	v_fmac_f32_e32 v7, v168, v104
	v_fmac_f32_e32 v105, v168, v108
	v_fma_f32 v6, -v169, v105, v6
	v_cvt_pk_bf16_f32 v104, v7, v105
	v_fmac_f32_e32 v6, v168, v7
	v_fma_f32 v7, v169, v7, v130
	ds_write_b32 v205, v104 offset:11056
	v_fmac_f32_e32 v7, v168, v105
	v_fma_f32 v5, -v169, v7, v5
	v_fma_f32 v105, v169, v6, v129
	v_fmac_f32_e32 v105, v168, v7
	v_cvt_pk_bf16_f32 v104, v6, v7
	v_fmac_f32_e32 v5, v168, v6
	v_fma_f32 v129, -v169, v105, v4
	ds_write_b32 v205, v104 offset:10784
	s_nop 0
	v_cvt_pk_bf16_f32 v4, v5, v105
	v_fmac_f32_e32 v129, v168, v5
	v_fmac_f32_e32 v128, v169, v5
	ds_write_b32 v205, v4 offset:10512
	v_fmac_f32_e32 v128, v168, v105
	s_nop 0
	v_cvt_pk_bf16_f32 v4, v129, v128
	ds_write_b32 v205, v4 offset:10240
	s_waitcnt lgkmcnt(0)
	ds_read_b128 v[112:115], v204 offset:10240
	ds_read_b128 v[108:111], v204 offset:10304
	ds_read_b128 v[104:107], v204 offset:10368
	ds_read_b128 v[4:7], v204 offset:10432
	s_waitcnt lgkmcnt(0)
	ds_write_b128 v201, v[132:135]
	ds_write_b128 v201, v[136:139] offset:1280
	ds_write_b128 v201, v[140:143] offset:2560
	ds_write_b128 v202, v[148:151]
	ds_write_b128 v201, v[116:119] offset:5120
	ds_write_b128 v201, v[120:123] offset:6400
	ds_write_b128 v201, v[124:127] offset:7680
	ds_write_b128 v203, v[144:147]
	s_waitcnt lgkmcnt(0)
	ds_read_b128 v[0:3], v175 offset:48
	ds_read_b128 v[32:35], v175 offset:5168
	s_waitcnt lgkmcnt(13)
	v_mfma_f32_16x16x32_bf16 v[20:23], v[112:115], v[60:63], v[20:23]
	s_waitcnt lgkmcnt(1)
	v_fma_f32 v3, -v169, v128, v3
	s_waitcnt lgkmcnt(0)
	v_fma_f32 v35, v169, v129, v35
	v_fmac_f32_e32 v3, v168, v129
	v_fmac_f32_e32 v35, v168, v128
	v_fma_f32 v2, -v169, v35, v2
	v_cvt_pk_bf16_f32 v36, v3, v35
	v_fmac_f32_e32 v2, v168, v3
	v_fma_f32 v3, v169, v3, v34
	ds_write_b32 v205, v36 offset:14320
	v_fmac_f32_e32 v3, v168, v35
	v_fma_f32 v1, -v169, v3, v1
	v_fma_f32 v33, v169, v2, v33
	v_fmac_f32_e32 v33, v168, v3
	v_cvt_pk_bf16_f32 v34, v2, v3
	v_fmac_f32_e32 v1, v168, v2
	v_fma_f32 v38, -v169, v33, v0
	ds_write_b32 v205, v34 offset:14048
	v_mfma_f32_16x16x32_bf16 v[20:23], v[108:111], v[56:59], v[20:23]
	v_cvt_pk_bf16_f32 v0, v1, v33
	v_fmac_f32_e32 v38, v168, v1
	v_fmac_f32_e32 v32, v169, v1
	ds_write_b32 v205, v0 offset:13776
	v_fmac_f32_e32 v32, v168, v33
	v_mfma_f32_16x16x32_bf16 v[20:23], v[104:107], v[72:75], v[20:23]
	v_cvt_pk_bf16_f32 v0, v38, v32
	ds_write_b32 v205, v0 offset:13504
	ds_read_b128 v[0:3], v175 offset:32
	ds_read_b128 v[34:37], v175 offset:5152
	v_mfma_f32_16x16x32_bf16 v[4:7], v[4:7], v[76:79], v[20:23]
	s_waitcnt lgkmcnt(1)
	v_fma_f32 v3, -v169, v32, v3
	s_waitcnt lgkmcnt(0)
	v_fma_f32 v33, v169, v38, v37
	v_fmac_f32_e32 v3, v168, v38
	v_fmac_f32_e32 v33, v168, v32
	v_fma_f32 v2, -v169, v33, v2
	v_cvt_pk_bf16_f32 v32, v3, v33
	v_fmac_f32_e32 v2, v168, v3
	v_fma_f32 v3, v169, v3, v36
	ds_write_b32 v205, v32 offset:13232
	v_fmac_f32_e32 v3, v168, v33
	v_fma_f32 v1, -v169, v3, v1
	v_fma_f32 v33, v169, v2, v35
	v_cvt_pk_bf16_f32 v32, v2, v3
	v_fmac_f32_e32 v33, v168, v3
	ds_write_b32 v205, v32 offset:12960
	v_fmac_f32_e32 v1, v168, v2
	v_fma_f32 v32, -v169, v33, v0
	s_nop 0
	v_cvt_pk_bf16_f32 v0, v1, v33
	v_fmac_f32_e32 v32, v168, v1
	v_fmac_f32_e32 v34, v169, v1
	ds_write_b32 v205, v0 offset:12688
	v_fmac_f32_e32 v34, v168, v33
	s_nop 0
	v_cvt_pk_bf16_f32 v0, v32, v34
	ds_write_b32 v205, v0 offset:12416
	ds_read_b128 v[0:3], v175 offset:16
	ds_read_b128 v[36:39], v175 offset:5136
	s_waitcnt lgkmcnt(1)
	v_fma_f32 v3, -v169, v34, v3
	v_fmac_f32_e32 v3, v168, v32
	s_waitcnt lgkmcnt(0)
	v_fma_f32 v32, v169, v32, v39
	v_fmac_f32_e32 v32, v168, v34
	v_fma_f32 v2, -v169, v32, v2
	v_cvt_pk_bf16_f32 v33, v3, v32
	v_fmac_f32_e32 v2, v168, v3
	v_fma_f32 v3, v169, v3, v38
	v_fmac_f32_e32 v3, v168, v32
	ds_write_b32 v205, v33 offset:12144
	v_fma_f32 v1, -v169, v3, v1
	v_cvt_pk_bf16_f32 v32, v2, v3
	v_fmac_f32_e32 v1, v168, v2
	v_fma_f32 v2, v169, v2, v37
	v_fmac_f32_e32 v2, v168, v3
	v_fma_f32 v37, -v169, v2, v0
	ds_write_b32 v205, v32 offset:11872
	s_nop 0
	v_cvt_pk_bf16_f32 v3, v1, v2
	v_fmac_f32_e32 v37, v168, v1
	v_fmac_f32_e32 v36, v169, v1
	ds_write_b32 v205, v3 offset:11600
	v_fmac_f32_e32 v36, v168, v2
	s_nop 0
	v_cvt_pk_bf16_f32 v0, v37, v36
	ds_write_b32 v205, v0 offset:11328
	ds_read_b128 v[0:3], v175
	ds_read_b128 v[32:35], v175 offset:5120
	s_waitcnt lgkmcnt(1)
	v_fma_f32 v3, -v169, v36, v3
	s_waitcnt lgkmcnt(0)
	v_fma_f32 v35, v169, v37, v35
	v_fmac_f32_e32 v3, v168, v37
	v_fmac_f32_e32 v35, v168, v36
	v_fma_f32 v2, -v169, v35, v2
	v_cvt_pk_bf16_f32 v36, v3, v35
	v_fmac_f32_e32 v2, v168, v3
	v_fma_f32 v3, v169, v3, v34
	v_fmac_f32_e32 v3, v168, v35
	ds_write_b32 v205, v36 offset:11056
	v_fma_f32 v1, -v169, v3, v1
	v_cvt_pk_bf16_f32 v34, v2, v3
	v_fmac_f32_e32 v1, v168, v2
	v_fma_f32 v2, v169, v2, v33
	v_fmac_f32_e32 v2, v168, v3
	v_fma_f32 v0, -v169, v2, v0
	ds_write_b32 v205, v34 offset:10784
	s_nop 0
	v_cvt_pk_bf16_f32 v3, v1, v2
	v_fmac_f32_e32 v0, v168, v1
	ds_write_b32 v205, v3 offset:10512
	v_fmac_f32_e32 v32, v169, v1
	v_fmac_f32_e32 v32, v168, v2
	v_cvt_pk_bf16_f32 v0, v0, v32
	ds_write_b32 v205, v0 offset:10240
	s_waitcnt lgkmcnt(0)
	ds_read_b128 v[0:3], v204 offset:10240
	ds_read_b128 v[32:35], v204 offset:10304
	s_waitcnt lgkmcnt(1)
	v_mfma_f32_16x16x32_bf16 v[0:3], v[0:3], v[60:63], v[24:27]
	s_waitcnt lgkmcnt(0)
	v_mfma_f32_16x16x32_bf16 v[0:3], v[32:35], v[56:59], v[0:3]
	s_nop 0
	ds_read_b128 v[24:27], v204 offset:10368
	ds_read_b128 v[32:35], v204 offset:10432
	s_waitcnt lgkmcnt(0)
	s_waitcnt lgkmcnt(1)
	v_mfma_f32_16x16x32_bf16 v[24:27], v[24:27], v[72:75], v[0:3]
	s_nop 2
	v_or_b32_e32 v0, s7, v194
	v_or_b32_e32 v2, s2, v173
	v_ashrrev_i32_e32 v1, 31, v0
	v_lshlrev_b32_e32 v3, 2, v2
	v_lshlrev_b64 v[36:37], 11, v[0:1]
	v_lshlrev_b32_e32 v2, 1, v2
	v_or_b32_e32 v36, v36, v2
	v_lshl_add_u64 v[38:39], s[60:61], 0, v[36:37]
	global_load_ushort v38, v[38:39], off
	s_nop 0
	global_load_dword v1, v3, s[46:47]
	s_waitcnt lgkmcnt(0)
	v_mfma_f32_16x16x32_bf16 v[24:27], v[32:35], v[76:79], v[24:27]
	v_or_b32_e32 v32, 1, v0
	v_ashrrev_i32_e32 v33, 31, v32
	v_lshlrev_b64 v[32:33], 11, v[32:33]
	v_lshl_add_u64 v[34:35], s[38:39], 0, v[36:37]
	v_or_b32_e32 v32, v32, v2
	v_lshl_add_u64 v[36:37], s[60:61], 0, v[32:33]
	v_lshl_add_u64 v[32:33], s[38:39], 0, v[32:33]
	v_or_b32_e32 v20, 17, v0
	v_ashrrev_i32_e32 v21, 31, v20
	v_lshlrev_b64 v[20:21], 11, v[20:21]
	v_or_b32_e32 v20, v20, v2
	s_waitcnt vmcnt(1)
	v_lshlrev_b32_e32 v3, 16, v38
	s_waitcnt vmcnt(0)
	v_fma_f32 v3, v1, v3, v24
	v_mul_f32_e32 v24, 0x3d372713, v3
	v_mul_f32_e32 v24, v3, v24
	v_fma_f32 v24, v3, v24, v3
	v_mul_f32_e32 v24, 0x3f4c422a, v24
	v_mul_f32_e32 v24, 0x4038aa3b, v24
	v_exp_f32_e32 v24, v24
	v_mul_f32_e32 v3, 0.5, v3
	v_add_f32_e32 v24, 1.0, v24
	v_rcp_f32_e32 v24, v24
	s_nop 0
	v_fma_f32 v24, v24, -2.0, 1.0
	v_add_f32_e32 v24, 1.0, v24
	v_mul_f32_e32 v3, v3, v24
	v_cvt_pk_bf16_f32 v3, v3, v177
	global_store_short v[34:35], v3, off
	global_load_ushort v3, v[36:37], off
	v_or_b32_e32 v24, 2, v0
	s_waitcnt vmcnt(0)
	v_lshlrev_b32_e32 v3, 16, v3
	v_fma_f32 v3, v1, v3, v25
	v_mul_f32_e32 v25, 0x3d372713, v3
	v_mul_f32_e32 v25, v3, v25
	v_fma_f32 v25, v3, v25, v3
	v_mul_f32_e32 v25, 0x3f4c422a, v25
	v_mul_f32_e32 v25, 0x4038aa3b, v25
	v_exp_f32_e32 v34, v25
	v_ashrrev_i32_e32 v25, 31, v24
	v_lshlrev_b64 v[24:25], 11, v[24:25]
	v_mul_f32_e32 v3, 0.5, v3
	v_add_f32_e32 v34, 1.0, v34
	v_rcp_f32_e32 v36, v34
	v_or_b32_e32 v24, v24, v2
	v_lshl_add_u64 v[34:35], s[60:61], 0, v[24:25]
	v_lshl_add_u64 v[24:25], s[38:39], 0, v[24:25]
	v_fma_f32 v36, v36, -2.0, 1.0
	v_add_f32_e32 v36, 1.0, v36
	v_mul_f32_e32 v3, v3, v36
	v_cvt_pk_bf16_f32 v3, v3, v177
	global_store_short v[32:33], v3, off
	global_load_ushort v3, v[34:35], off
	v_or_b32_e32 v32, 3, v0
	v_ashrrev_i32_e32 v33, 31, v32
	v_lshlrev_b64 v[32:33], 11, v[32:33]
	v_or_b32_e32 v32, v32, v2
	v_lshl_add_u64 v[34:35], s[60:61], 0, v[32:33]
	v_lshl_add_u64 v[32:33], s[38:39], 0, v[32:33]
	s_waitcnt vmcnt(0)
	v_lshlrev_b32_e32 v3, 16, v3
	v_fma_f32 v3, v1, v3, v26
	v_mul_f32_e32 v26, 0x3d372713, v3
	v_mul_f32_e32 v26, v3, v26
	v_fma_f32 v26, v3, v26, v3
	v_mul_f32_e32 v26, 0x3f4c422a, v26
	v_mul_f32_e32 v26, 0x4038aa3b, v26
	v_exp_f32_e32 v26, v26
	v_mul_f32_e32 v3, 0.5, v3
	v_add_f32_e32 v26, 1.0, v26
	v_rcp_f32_e32 v26, v26
	s_nop 0
	v_fma_f32 v26, v26, -2.0, 1.0
	v_add_f32_e32 v26, 1.0, v26
	v_mul_f32_e32 v3, v3, v26
	v_cvt_pk_bf16_f32 v3, v3, v177
	global_store_short v[24:25], v3, off
	global_load_ushort v3, v[34:35], off
	v_or_b32_e32 v24, 16, v0
	v_ashrrev_i32_e32 v25, 31, v24
	v_lshlrev_b64 v[24:25], 11, v[24:25]
	v_or_b32_e32 v24, v24, v2
	v_lshl_add_u64 v[34:35], s[60:61], 0, v[24:25]
	v_lshl_add_u64 v[22:23], s[38:39], 0, v[24:25]
	v_lshl_add_u64 v[24:25], s[60:61], 0, v[20:21]
	v_lshl_add_u64 v[20:21], s[38:39], 0, v[20:21]
	s_waitcnt vmcnt(0)
	v_lshlrev_b32_e32 v3, 16, v3
	v_fmac_f32_e32 v27, v1, v3
	v_mul_f32_e32 v3, 0x3d372713, v27
	v_mul_f32_e32 v3, v27, v3
	v_fma_f32 v3, v27, v3, v27
	v_mul_f32_e32 v3, 0x3f4c422a, v3
	v_mul_f32_e32 v3, 0x4038aa3b, v3
	v_exp_f32_e32 v3, v3
	v_mul_f32_e32 v26, 0.5, v27
	v_add_f32_e32 v3, 1.0, v3
	v_rcp_f32_e32 v3, v3
	s_nop 0
	v_fma_f32 v3, v3, -2.0, 1.0
	v_add_f32_e32 v3, 1.0, v3
	v_mul_f32_e32 v3, v26, v3
	v_cvt_pk_bf16_f32 v3, v3, v177
	global_store_short v[32:33], v3, off
	global_load_ushort v3, v[34:35], off
	s_waitcnt vmcnt(0)
	v_lshlrev_b32_e32 v3, 16, v3
	v_fma_f32 v3, v1, v3, v4
	v_mul_f32_e32 v4, 0x3d372713, v3
	v_mul_f32_e32 v4, v3, v4
	v_fma_f32 v4, v3, v4, v3
	v_mul_f32_e32 v4, 0x3f4c422a, v4
	v_mul_f32_e32 v4, 0x4038aa3b, v4
	v_exp_f32_e32 v4, v4
	v_mul_f32_e32 v3, 0.5, v3
	v_add_f32_e32 v4, 1.0, v4
	v_rcp_f32_e32 v4, v4
	s_nop 0
	v_fma_f32 v4, v4, -2.0, 1.0
	v_add_f32_e32 v4, 1.0, v4
	v_mul_f32_e32 v3, v3, v4
	v_cvt_pk_bf16_f32 v3, v3, v177
	global_store_short v[22:23], v3, off
	global_load_ushort v3, v[24:25], off
	v_or_b32_e32 v4, 18, v0
	s_waitcnt vmcnt(0)
	v_lshlrev_b32_e32 v3, 16, v3
	v_fma_f32 v3, v1, v3, v5
	v_mul_f32_e32 v5, 0x3d372713, v3
	v_mul_f32_e32 v5, v3, v5
	v_fma_f32 v5, v3, v5, v3
	v_mul_f32_e32 v5, 0x3f4c422a, v5
	v_mul_f32_e32 v5, 0x4038aa3b, v5
	v_exp_f32_e32 v22, v5
	v_ashrrev_i32_e32 v5, 31, v4
	v_lshlrev_b64 v[4:5], 11, v[4:5]
	v_mul_f32_e32 v3, 0.5, v3
	v_add_f32_e32 v22, 1.0, v22
	v_rcp_f32_e32 v24, v22
	v_or_b32_e32 v4, v4, v2
	v_lshl_add_u64 v[22:23], s[60:61], 0, v[4:5]
	v_lshl_add_u64 v[4:5], s[38:39], 0, v[4:5]
	v_fma_f32 v24, v24, -2.0, 1.0
	v_add_f32_e32 v24, 1.0, v24
	v_mul_f32_e32 v3, v3, v24
	v_cvt_pk_bf16_f32 v3, v3, v177
	global_store_short v[20:21], v3, off
	global_load_ushort v3, v[22:23], off
	v_or_b32_e32 v20, 19, v0
	v_ashrrev_i32_e32 v21, 31, v20
	v_lshlrev_b64 v[24:25], 11, v[20:21]
	v_or_b32_e32 v24, v24, v2
	v_lshl_add_u64 v[20:21], s[60:61], 0, v[24:25]
	s_waitcnt vmcnt(0)
	v_lshlrev_b32_e32 v3, 16, v3
	v_fma_f32 v3, v1, v3, v6
	v_mul_f32_e32 v6, 0x3d372713, v3
	v_mul_f32_e32 v6, v3, v6
	v_fma_f32 v6, v3, v6, v3
	v_mul_f32_e32 v6, 0x3f4c422a, v6
	v_mul_f32_e32 v6, 0x4038aa3b, v6
	v_exp_f32_e32 v6, v6
	v_mul_f32_e32 v3, 0.5, v3
	v_add_f32_e32 v6, 1.0, v6
	v_rcp_f32_e32 v6, v6
	s_nop 0
	v_fma_f32 v6, v6, -2.0, 1.0
	v_add_f32_e32 v6, 1.0, v6
	v_mul_f32_e32 v3, v3, v6
	v_cvt_pk_bf16_f32 v3, v3, v177
	global_store_short v[4:5], v3, off
	global_load_ushort v3, v[20:21], off
	v_or_b32_e32 v4, 32, v0
	v_ashrrev_i32_e32 v5, 31, v4
	v_lshlrev_b64 v[26:27], 11, v[4:5]
	v_or_b32_e32 v26, v26, v2
	v_lshl_add_u64 v[4:5], s[38:39], 0, v[24:25]
	v_lshl_add_u64 v[24:25], s[60:61], 0, v[26:27]
	v_mfma_f32_16x16x32_bf16 v[20:23], v[100:103], v[60:63], v[28:31]
	s_waitcnt vmcnt(0)
	v_lshlrev_b32_e32 v3, 16, v3
	v_fmac_f32_e32 v7, v1, v3
	v_mul_f32_e32 v3, 0x3d372713, v7
	v_mul_f32_e32 v3, v7, v3
	v_fma_f32 v3, v7, v3, v7
	v_mul_f32_e32 v3, 0x3f4c422a, v3
	v_mul_f32_e32 v3, 0x4038aa3b, v3
	v_exp_f32_e32 v3, v3
	v_mul_f32_e32 v6, 0.5, v7
	v_mfma_f32_16x16x32_bf16 v[20:23], v[96:99], v[56:59], v[20:23]
	v_add_f32_e32 v3, 1.0, v3
	v_rcp_f32_e32 v3, v3
	v_mfma_f32_16x16x32_bf16 v[20:23], v[92:95], v[72:75], v[20:23]
	v_fma_f32 v3, v3, -2.0, 1.0
	v_add_f32_e32 v3, 1.0, v3
	v_mul_f32_e32 v3, v6, v3
	v_cvt_pk_bf16_f32 v3, v3, v177
	global_store_short v[4:5], v3, off
	global_load_ushort v3, v[24:25], off
	v_mfma_f32_16x16x32_bf16 v[4:7], v[8:11], v[76:79], v[20:23]
	v_or_b32_e32 v8, 33, v0
	v_ashrrev_i32_e32 v9, 31, v8
	v_lshlrev_b64 v[8:9], 11, v[8:9]
	v_or_b32_e32 v8, v8, v2
	v_lshl_add_u64 v[10:11], s[38:39], 0, v[26:27]
	v_lshl_add_u64 v[20:21], s[60:61], 0, v[8:9]
	v_lshl_add_u64 v[8:9], s[38:39], 0, v[8:9]
	s_waitcnt vmcnt(0)
	v_lshlrev_b32_e32 v3, 16, v3
	v_fma_f32 v3, v1, v3, v4
	v_mul_f32_e32 v4, 0x3d372713, v3
	v_mul_f32_e32 v4, v3, v4
	v_fma_f32 v4, v3, v4, v3
	v_mul_f32_e32 v4, 0x3f4c422a, v4
	v_mul_f32_e32 v4, 0x4038aa3b, v4
	v_exp_f32_e32 v4, v4
	v_mul_f32_e32 v3, 0.5, v3
	v_add_f32_e32 v4, 1.0, v4
	v_rcp_f32_e32 v4, v4
	s_nop 0
	v_fma_f32 v4, v4, -2.0, 1.0
	v_add_f32_e32 v4, 1.0, v4
	v_mul_f32_e32 v3, v3, v4
	v_cvt_pk_bf16_f32 v3, v3, v177
	global_store_short v[10:11], v3, off
	global_load_ushort v3, v[20:21], off
	v_or_b32_e32 v4, 34, v0
	s_waitcnt vmcnt(0)
	v_lshlrev_b32_e32 v3, 16, v3
	v_fma_f32 v3, v1, v3, v5
	v_mul_f32_e32 v5, 0x3d372713, v3
	v_mul_f32_e32 v5, v3, v5
	v_fma_f32 v5, v3, v5, v3
	v_mul_f32_e32 v5, 0x3f4c422a, v5
	v_mul_f32_e32 v5, 0x4038aa3b, v5
	v_exp_f32_e32 v10, v5
	v_ashrrev_i32_e32 v5, 31, v4
	v_lshlrev_b64 v[4:5], 11, v[4:5]
	v_mul_f32_e32 v3, 0.5, v3
	v_add_f32_e32 v10, 1.0, v10
	v_rcp_f32_e32 v20, v10
	v_or_b32_e32 v4, v4, v2
	v_lshl_add_u64 v[10:11], s[60:61], 0, v[4:5]
	v_lshl_add_u64 v[4:5], s[38:39], 0, v[4:5]
	v_fma_f32 v20, v20, -2.0, 1.0
	v_add_f32_e32 v20, 1.0, v20
	v_mul_f32_e32 v3, v3, v20
	v_cvt_pk_bf16_f32 v3, v3, v177
	global_store_short v[8:9], v3, off
	global_load_ushort v3, v[10:11], off
	v_or_b32_e32 v8, 35, v0
	v_ashrrev_i32_e32 v9, 31, v8
	v_lshlrev_b64 v[20:21], 11, v[8:9]
	v_or_b32_e32 v20, v20, v2
	v_lshl_add_u64 v[8:9], s[60:61], 0, v[20:21]
	s_waitcnt vmcnt(0)
	v_lshlrev_b32_e32 v3, 16, v3
	v_fma_f32 v3, v1, v3, v6
	v_mul_f32_e32 v6, 0x3d372713, v3
	v_mul_f32_e32 v6, v3, v6
	v_fma_f32 v6, v3, v6, v3
	v_mul_f32_e32 v6, 0x3f4c422a, v6
	v_mul_f32_e32 v6, 0x4038aa3b, v6
	v_exp_f32_e32 v6, v6
	v_mul_f32_e32 v3, 0.5, v3
	v_add_f32_e32 v6, 1.0, v6
	v_rcp_f32_e32 v6, v6
	s_nop 0
	v_fma_f32 v6, v6, -2.0, 1.0
	v_add_f32_e32 v6, 1.0, v6
	v_mul_f32_e32 v3, v3, v6
	v_cvt_pk_bf16_f32 v3, v3, v177
	global_store_short v[4:5], v3, off
	global_load_ushort v3, v[8:9], off
	v_or_b32_e32 v4, 48, v0
	v_ashrrev_i32_e32 v5, 31, v4
	v_lshlrev_b64 v[22:23], 11, v[4:5]
	v_or_b32_e32 v22, v22, v2
	v_lshl_add_u64 v[4:5], s[38:39], 0, v[20:21]
	v_mfma_f32_16x16x32_bf16 v[8:11], v[88:91], v[60:63], v[16:19]
	s_waitcnt vmcnt(0)
	v_lshlrev_b32_e32 v3, 16, v3
	v_fmac_f32_e32 v7, v1, v3
	v_mul_f32_e32 v3, 0x3d372713, v7
	v_mul_f32_e32 v3, v7, v3
	v_fma_f32 v3, v7, v3, v7
	v_mul_f32_e32 v3, 0x3f4c422a, v3
	v_mul_f32_e32 v3, 0x4038aa3b, v3
	v_exp_f32_e32 v3, v3
	v_mul_f32_e32 v6, 0.5, v7
	v_lshl_add_u64 v[16:17], s[60:61], 0, v[22:23]
	v_mfma_f32_16x16x32_bf16 v[8:11], v[84:87], v[56:59], v[8:11]
	v_add_f32_e32 v3, 1.0, v3
	v_rcp_f32_e32 v3, v3
	v_mfma_f32_16x16x32_bf16 v[8:11], v[80:83], v[72:75], v[8:11]
	v_fma_f32 v3, v3, -2.0, 1.0
	v_add_f32_e32 v3, 1.0, v3
	v_mul_f32_e32 v3, v6, v3
	v_cvt_pk_bf16_f32 v3, v3, v177
	global_store_short v[4:5], v3, off
	global_load_ushort v3, v[16:17], off
	v_mfma_f32_16x16x32_bf16 v[4:7], v[12:15], v[76:79], v[8:11]
	s_waitcnt vmcnt(0)
	v_lshlrev_b32_e32 v3, 16, v3
	s_nop 5
	v_fma_f32 v3, v1, v3, v4
	v_mul_f32_e32 v4, 0x3d372713, v3
	v_mul_f32_e32 v4, v3, v4
	v_fma_f32 v4, v3, v4, v3
	v_mul_f32_e32 v4, 0x3f4c422a, v4
	v_mul_f32_e32 v4, 0x4038aa3b, v4
	v_exp_f32_e32 v4, v4
	v_or_b32_e32 v8, 49, v0
	v_ashrrev_i32_e32 v9, 31, v8
	v_lshlrev_b64 v[8:9], 11, v[8:9]
	v_add_f32_e32 v4, 1.0, v4
	v_rcp_f32_e32 v4, v4
	v_mul_f32_e32 v3, 0.5, v3
	v_or_b32_e32 v8, v8, v2
	v_lshl_add_u64 v[10:11], s[38:39], 0, v[22:23]
	v_fma_f32 v4, v4, -2.0, 1.0
	v_add_f32_e32 v4, 1.0, v4
	v_mul_f32_e32 v3, v3, v4
	v_lshl_add_u64 v[12:13], s[60:61], 0, v[8:9]
	v_cvt_pk_bf16_f32 v3, v3, v177
	global_store_short v[10:11], v3, off
	global_load_ushort v3, v[12:13], off
	v_or_b32_e32 v4, 50, v0
	v_lshl_add_u64 v[8:9], s[38:39], 0, v[8:9]
	s_waitcnt vmcnt(0)
	v_lshlrev_b32_e32 v3, 16, v3
	v_fma_f32 v3, v1, v3, v5
	v_mul_f32_e32 v5, 0x3d372713, v3
	v_mul_f32_e32 v5, v3, v5
	v_fma_f32 v5, v3, v5, v3
	v_mul_f32_e32 v5, 0x3f4c422a, v5
	v_mul_f32_e32 v5, 0x4038aa3b, v5
	v_exp_f32_e32 v10, v5
	v_ashrrev_i32_e32 v5, 31, v4
	v_lshlrev_b64 v[4:5], 11, v[4:5]
	v_mul_f32_e32 v3, 0.5, v3
	v_add_f32_e32 v10, 1.0, v10
	v_rcp_f32_e32 v12, v10
	v_or_b32_e32 v4, v4, v2
	v_lshl_add_u64 v[10:11], s[60:61], 0, v[4:5]
	v_fma_f32 v12, v12, -2.0, 1.0
	v_add_f32_e32 v12, 1.0, v12
	v_mul_f32_e32 v3, v3, v12
	v_cvt_pk_bf16_f32 v3, v3, v177
	global_store_short v[8:9], v3, off
	global_load_ushort v3, v[10:11], off
	v_or_b32_e32 v8, 51, v0
	v_ashrrev_i32_e32 v9, 31, v8
	v_lshlrev_b64 v[8:9], 11, v[8:9]
	v_or_b32_e32 v8, v8, v2
	s_waitcnt vmcnt(0)
	v_lshlrev_b32_e32 v0, 16, v3
	v_fma_f32 v0, v1, v0, v6
	v_mul_f32_e32 v3, 0x3d372713, v0
	v_mul_f32_e32 v3, v0, v3
	v_fma_f32 v3, v0, v3, v0
	v_mul_f32_e32 v3, 0x3f4c422a, v3
	v_mul_f32_e32 v3, 0x4038aa3b, v3
	v_exp_f32_e32 v3, v3
	v_mul_f32_e32 v0, 0.5, v0
	v_add_f32_e32 v2, 1.0, v3
	v_rcp_f32_e32 v6, v2
	v_lshl_add_u64 v[2:3], s[38:39], 0, v[4:5]
	v_lshl_add_u64 v[4:5], s[60:61], 0, v[8:9]
	v_fma_f32 v6, v6, -2.0, 1.0
	v_add_f32_e32 v6, 1.0, v6
	v_mul_f32_e32 v0, v0, v6
	v_cvt_pk_bf16_f32 v0, v0, v177
	global_store_short v[2:3], v0, off
	global_load_ushort v0, v[4:5], off
	s_waitcnt vmcnt(0)
	v_lshlrev_b32_e32 v0, 16, v0
	v_fmac_f32_e32 v7, v1, v0
	v_mul_f32_e32 v0, 0x3d372713, v7
	v_mul_f32_e32 v0, v7, v0
	v_fma_f32 v0, v7, v0, v7
	v_mul_f32_e32 v0, 0x3f4c422a, v0
	v_mul_f32_e32 v0, 0x4038aa3b, v0
	v_exp_f32_e32 v0, v0
	v_mul_f32_e32 v3, 0.5, v7
	v_add_f32_e32 v0, 1.0, v0
	v_rcp_f32_e32 v2, v0
	v_lshl_add_u64 v[0:1], s[38:39], 0, v[8:9]
	v_fma_f32 v2, v2, -2.0, 1.0
	v_add_f32_e32 v2, 1.0, v2
	v_mul_f32_e32 v2, v3, v2
	v_cvt_pk_bf16_f32 v2, v2, v177
	global_store_short v[0:1], v2, off
	s_cbranch_scc1 .LBB0_1562

.LBB0_1546:
	s_or_b64 exec, exec, s[4:5]
	v_lshl_or_b32 v176, s8, 12, v200
	v_lshl_add_u64 v[238:239], v[186:187], 0, v[176:177]
	v_lshl_add_u64 v[164:165], v[188:189], 0, v[176:177]
	global_load_dwordx4 v[214:217], v[238:239], off
	global_load_dwordx4 v[218:221], v[164:165], off
	global_load_dwordx4 v[222:225], v[238:239], off offset:64
	global_load_dwordx4 v[226:229], v[164:165], off offset:64
	global_load_dwordx4 v[230:233], v[238:239], off offset:128
	global_load_dwordx4 v[234:237], v[164:165], off offset:128
	global_load_dwordx4 v[92:95], v[238:239], off offset:192
	global_load_dwordx4 v[168:171], v[164:165], off offset:192
	s_waitcnt vmcnt(6)
	v_xor_b32_e32 v218, 0x80000000, v218
	v_xor_b32_e32 v219, 0x80000000, v219
	v_xor_b32_e32 v220, 0x80000000, v220
	v_xor_b32_e32 v221, 0x80000000, v221
	v_cvt_pk_bf16_f32 v52, v214, v218
	v_cvt_pk_bf16_f32 v53, v215, v219
	v_cvt_pk_bf16_f32 v54, v216, v220
	v_cvt_pk_bf16_f32 v55, v217, v221
	s_waitcnt vmcnt(4)
	v_xor_b32_e32 v226, 0x80000000, v226
	v_xor_b32_e32 v227, 0x80000000, v227
	v_xor_b32_e32 v228, 0x80000000, v228
	v_xor_b32_e32 v229, 0x80000000, v229
	v_cvt_pk_bf16_f32 v56, v222, v226
	v_cvt_pk_bf16_f32 v57, v223, v227
	v_cvt_pk_bf16_f32 v58, v224, v228
	v_cvt_pk_bf16_f32 v59, v225, v229
	s_waitcnt vmcnt(2)
	v_xor_b32_e32 v234, 0x80000000, v234
	v_xor_b32_e32 v235, 0x80000000, v235
	v_xor_b32_e32 v236, 0x80000000, v236
	v_xor_b32_e32 v237, 0x80000000, v237
	v_cvt_pk_bf16_f32 v60, v230, v234
	v_cvt_pk_bf16_f32 v61, v231, v235
	v_cvt_pk_bf16_f32 v62, v232, v236
	v_cvt_pk_bf16_f32 v63, v233, v237
	s_waitcnt vmcnt(0)
	v_xor_b32_e32 v168, 0x80000000, v168
	v_xor_b32_e32 v169, 0x80000000, v169
	v_xor_b32_e32 v170, 0x80000000, v170
	v_xor_b32_e32 v171, 0x80000000, v171
	v_cvt_pk_bf16_f32 v92, v92, v168
	v_cvt_pk_bf16_f32 v93, v93, v169
	v_cvt_pk_bf16_f32 v94, v94, v170
	v_cvt_pk_bf16_f32 v95, v95, v171
	s_ashr_i32 s9, s6, 5
	s_and_b32 s4, s9, -2
	s_lshl_b32 s2, s2, 3
	s_ashr_i32 s5, s4, 31
	v_lshl_add_u64 v[192:193], v[184:185], 0, s[2:3]
	s_lshl_b64 s[4:5], s[4:5], 15
	v_lshl_add_u64 v[206:207], v[192:193], 0, s[4:5]
	v_mfma_f32_16x16x32_bf16 v[24:27], v[0:3], v[20:23], 0
	s_or_b32 s10, s8, 64
	v_lshl_or_b32 v176, s10, 12, v195
	v_mfma_f32_16x16x32_bf16 v[64:67], v[0:3], v[16:19], 0
	global_load_dwordx2 v[206:207], v[206:207], off
	v_mfma_f32_16x16x32_bf16 v[68:71], v[0:3], v[28:31], 0
	v_mfma_f32_16x16x32_bf16 v[72:75], v[0:3], v[32:35], 0
	v_mfma_f32_16x16x32_bf16 v[76:79], v[0:3], v[36:39], 0
	v_mfma_f32_16x16x32_bf16 v[80:83], v[0:3], v[40:43], 0
	v_mfma_f32_16x16x32_bf16 v[84:87], v[0:3], v[44:47], 0
	v_mfma_f32_16x16x32_bf16 v[88:91], v[0:3], v[48:51], 0
	ds_write_b128 v201, v[24:27]
	ds_write_b128 v201, v[64:67] offset:1280
	s_nop 0
	ds_write_b128 v201, v[68:71] offset:2560
	ds_write_b128 v202, v[72:75]
	ds_write_b128 v201, v[76:79] offset:5120
	ds_write_b128 v201, v[80:83] offset:6400
	ds_write_b128 v201, v[84:87] offset:7680
	ds_write_b128 v203, v[88:91]
	s_waitcnt lgkmcnt(0)
	ds_read_b128 v[24:27], v175
	ds_read_b128 v[70:73], v175 offset:5120
	v_mfma_f32_16x16x32_bf16 v[96:99], v[4:7], v[20:23], 0
	s_waitcnt vmcnt(0) lgkmcnt(1)
	v_fma_f32 v24, -v191, v207, v24
	s_waitcnt lgkmcnt(0)
	v_fma_f32 v68, v191, v206, v70
	v_fmac_f32_e32 v24, v190, v206
	v_fmac_f32_e32 v68, v190, v207
	v_fma_f32 v25, -v191, v68, v25
	v_cvt_pk_bf16_f32 v69, v24, v68
	v_fmac_f32_e32 v25, v190, v24
	v_fma_f32 v24, v191, v24, v71
	ds_write_b32 v205, v69 offset:10240
	v_fmac_f32_e32 v24, v190, v68
	v_fma_f32 v26, -v191, v24, v26
	v_fma_f32 v69, v191, v25, v72
	v_fmac_f32_e32 v69, v190, v24
	v_cvt_pk_bf16_f32 v68, v25, v24
	v_fmac_f32_e32 v26, v190, v25
	v_fma_f32 v72, -v191, v69, v27
	ds_write_b32 v205, v68 offset:10512
	v_mfma_f32_16x16x32_bf16 v[100:103], v[4:7], v[16:19], 0
	v_cvt_pk_bf16_f32 v24, v26, v69
	v_fmac_f32_e32 v72, v190, v26
	v_fmac_f32_e32 v73, v191, v26
	ds_write_b32 v205, v24 offset:10784
	v_fmac_f32_e32 v73, v190, v69
	v_mfma_f32_16x16x32_bf16 v[104:107], v[4:7], v[28:31], 0
	v_cvt_pk_bf16_f32 v24, v72, v73
	ds_write_b32 v205, v24 offset:11056
	ds_read_b128 v[24:27], v175 offset:16
	ds_read_b128 v[74:77], v175 offset:5136
	v_mfma_f32_16x16x32_bf16 v[108:111], v[4:7], v[32:35], 0
	s_waitcnt lgkmcnt(1)
	v_fma_f32 v24, -v191, v73, v24
	s_waitcnt lgkmcnt(0)
	v_fma_f32 v74, v191, v72, v74
	v_fmac_f32_e32 v24, v190, v72
	v_fmac_f32_e32 v74, v190, v73
	v_fma_f32 v25, -v191, v74, v25
	v_cvt_pk_bf16_f32 v72, v24, v74
	v_fmac_f32_e32 v25, v190, v24
	v_fma_f32 v24, v191, v24, v75
	ds_write_b32 v205, v72 offset:11328
	v_fmac_f32_e32 v24, v190, v74
	v_fma_f32 v26, -v191, v24, v26
	v_fma_f32 v73, v191, v25, v76
	v_fmac_f32_e32 v73, v190, v24
	v_cvt_pk_bf16_f32 v72, v25, v24
	v_fmac_f32_e32 v26, v190, v25
	v_fma_f32 v76, -v191, v73, v27
	ds_write_b32 v205, v72 offset:11600
	v_mfma_f32_16x16x32_bf16 v[112:115], v[4:7], v[36:39], 0
	v_cvt_pk_bf16_f32 v24, v26, v73
	v_fmac_f32_e32 v76, v190, v26
	v_fmac_f32_e32 v77, v191, v26
	ds_write_b32 v205, v24 offset:11872
	v_fmac_f32_e32 v77, v190, v73
	v_mfma_f32_16x16x32_bf16 v[116:119], v[4:7], v[40:43], 0
	v_cvt_pk_bf16_f32 v24, v76, v77
	ds_write_b32 v205, v24 offset:12144
	ds_read_b128 v[24:27], v175 offset:32
	ds_read_b128 v[78:81], v175 offset:5152
	v_mfma_f32_16x16x32_bf16 v[120:123], v[4:7], v[44:47], 0
	s_waitcnt lgkmcnt(1)
	v_fma_f32 v24, -v191, v77, v24
	s_waitcnt lgkmcnt(0)
	v_fma_f32 v78, v191, v76, v78
	v_fmac_f32_e32 v24, v190, v76
	v_fmac_f32_e32 v78, v190, v77
	v_fma_f32 v25, -v191, v78, v25
	v_cvt_pk_bf16_f32 v76, v24, v78
	v_fmac_f32_e32 v25, v190, v24
	v_fma_f32 v24, v191, v24, v79
	ds_write_b32 v205, v76 offset:12416
	v_fmac_f32_e32 v24, v190, v78
	v_fma_f32 v26, -v191, v24, v26
	v_fma_f32 v77, v191, v25, v80
	v_fmac_f32_e32 v77, v190, v24
	v_cvt_pk_bf16_f32 v76, v25, v24
	v_fmac_f32_e32 v26, v190, v25
	v_fma_f32 v80, -v191, v77, v27
	ds_write_b32 v205, v76 offset:12688
	v_mfma_f32_16x16x32_bf16 v[124:127], v[4:7], v[48:51], 0
	v_cvt_pk_bf16_f32 v24, v26, v77
	v_fmac_f32_e32 v80, v190, v26
	v_fmac_f32_e32 v81, v191, v26
	ds_write_b32 v205, v24 offset:12960
	v_fmac_f32_e32 v81, v190, v77
	v_mfma_f32_16x16x32_bf16 v[128:131], v[8:11], v[20:23], 0
	v_cvt_pk_bf16_f32 v24, v80, v81
	ds_write_b32 v205, v24 offset:13232
	ds_read_b128 v[24:27], v175 offset:48
	ds_read_b128 v[82:85], v175 offset:5168
	v_mfma_f32_16x16x32_bf16 v[132:135], v[8:11], v[16:19], 0
	s_waitcnt lgkmcnt(1)
	v_fma_f32 v24, -v191, v81, v24
	s_waitcnt lgkmcnt(0)
	v_fma_f32 v82, v191, v80, v82
	v_fmac_f32_e32 v24, v190, v80
	v_fmac_f32_e32 v82, v190, v81
	v_fma_f32 v25, -v191, v82, v25
	v_cvt_pk_bf16_f32 v80, v24, v82
	v_fmac_f32_e32 v25, v190, v24
	v_fma_f32 v24, v191, v24, v83
	ds_write_b32 v205, v80 offset:13504
	v_fmac_f32_e32 v24, v190, v82
	v_fma_f32 v26, -v191, v24, v26
	v_fma_f32 v81, v191, v25, v84
	v_fmac_f32_e32 v81, v190, v24
	v_cvt_pk_bf16_f32 v80, v25, v24
	v_fmac_f32_e32 v26, v190, v25
	v_fma_f32 v84, -v191, v81, v27
	ds_write_b32 v205, v80 offset:13776
	v_mfma_f32_16x16x32_bf16 v[136:139], v[8:11], v[28:31], 0
	v_cvt_pk_bf16_f32 v24, v26, v81
	v_fmac_f32_e32 v84, v190, v26
	v_fmac_f32_e32 v85, v191, v26
	ds_write_b32 v205, v24 offset:14048
	v_fmac_f32_e32 v85, v190, v81
	v_mfma_f32_16x16x32_bf16 v[140:143], v[8:11], v[32:35], 0
	v_cvt_pk_bf16_f32 v24, v84, v85
	ds_write_b32 v205, v24 offset:14320
	s_waitcnt lgkmcnt(0)
	ds_read_b128 v[24:27], v204 offset:10240
	ds_read_b128 v[86:89], v204 offset:10304
	ds_read_b128 v[206:209], v204 offset:10368
	ds_read_b128 v[210:213], v204 offset:10432
	s_waitcnt lgkmcnt(0)
	ds_write_b128 v201, v[96:99]
	ds_write_b128 v201, v[100:103] offset:1280
	ds_write_b128 v201, v[104:107] offset:2560
	ds_write_b128 v202, v[108:111]
	ds_write_b128 v201, v[112:115] offset:5120
	ds_write_b128 v201, v[116:119] offset:6400
	ds_write_b128 v201, v[120:123] offset:7680
	ds_write_b128 v203, v[124:127]
	s_waitcnt lgkmcnt(0)
	ds_read_b128 v[96:99], v175
	ds_read_b128 v[100:103], v175 offset:5120
	s_waitcnt lgkmcnt(13)
	v_mfma_f32_16x16x32_bf16 v[24:27], v[24:27], v[52:55], 0
	s_waitcnt lgkmcnt(1)
	v_fma_f32 v90, -v191, v85, v96
	s_waitcnt lgkmcnt(0)
	v_fma_f32 v91, v191, v84, v100
	v_fmac_f32_e32 v90, v190, v84
	v_fmac_f32_e32 v91, v190, v85
	v_fma_f32 v84, -v191, v91, v97
	v_cvt_pk_bf16_f32 v85, v90, v91
	v_fmac_f32_e32 v84, v190, v90
	v_fma_f32 v90, v191, v90, v101
	ds_write_b32 v205, v85 offset:10240
	v_fmac_f32_e32 v90, v190, v91
	v_fma_f32 v91, -v191, v90, v98
	v_fma_f32 v96, v191, v84, v102
	v_fmac_f32_e32 v96, v190, v90
	v_cvt_pk_bf16_f32 v85, v84, v90
	v_fmac_f32_e32 v91, v190, v84
	v_fma_f32 v84, -v191, v96, v99
	ds_write_b32 v205, v85 offset:10512
	v_mfma_f32_16x16x32_bf16 v[24:27], v[86:89], v[56:59], v[24:27]
	v_cvt_pk_bf16_f32 v85, v91, v96
	v_fmac_f32_e32 v84, v190, v91
	v_fmac_f32_e32 v103, v191, v91
	ds_write_b32 v205, v85 offset:10784
	v_fmac_f32_e32 v103, v190, v96
	v_mfma_f32_16x16x32_bf16 v[144:147], v[8:11], v[36:39], 0
	v_cvt_pk_bf16_f32 v85, v84, v103
	ds_write_b32 v205, v85 offset:11056
	ds_read_b128 v[96:99], v175 offset:16
	ds_read_b128 v[104:107], v175 offset:5136
	v_mfma_f32_16x16x32_bf16 v[148:151], v[8:11], v[40:43], 0
	s_waitcnt lgkmcnt(1)
	v_fma_f32 v85, -v191, v103, v96
	s_waitcnt lgkmcnt(0)
	v_fma_f32 v90, v191, v84, v104
	v_fmac_f32_e32 v85, v190, v84
	v_fmac_f32_e32 v90, v190, v103
	v_fma_f32 v84, -v191, v90, v97
	v_cvt_pk_bf16_f32 v91, v85, v90
	v_fmac_f32_e32 v84, v190, v85
	v_fma_f32 v85, v191, v85, v105
	ds_write_b32 v205, v91 offset:11328
	v_fmac_f32_e32 v85, v190, v90
	v_fma_f32 v91, -v191, v85, v98
	v_fma_f32 v96, v191, v84, v106
	v_fmac_f32_e32 v96, v190, v85
	v_cvt_pk_bf16_f32 v90, v84, v85
	v_fmac_f32_e32 v91, v190, v84
	v_fma_f32 v84, -v191, v96, v99
	ds_write_b32 v205, v90 offset:11600
	v_mfma_f32_16x16x32_bf16 v[152:155], v[8:11], v[44:47], 0
	v_cvt_pk_bf16_f32 v85, v91, v96
	v_fmac_f32_e32 v84, v190, v91
	v_fmac_f32_e32 v107, v191, v91
	ds_write_b32 v205, v85 offset:11872
	v_fmac_f32_e32 v107, v190, v96
	v_mfma_f32_16x16x32_bf16 v[156:159], v[8:11], v[48:51], 0
	v_cvt_pk_bf16_f32 v85, v84, v107
	ds_write_b32 v205, v85 offset:12144
	ds_read_b128 v[96:99], v175 offset:32
	ds_read_b128 v[100:103], v175 offset:5152
	v_mfma_f32_16x16x32_bf16 v[160:163], v[12:15], v[20:23], 0
	s_waitcnt lgkmcnt(1)
	v_fma_f32 v85, -v191, v107, v96
	s_waitcnt lgkmcnt(0)
	v_fma_f32 v86, v191, v84, v100
	v_fmac_f32_e32 v85, v190, v84
	v_fmac_f32_e32 v86, v190, v107
	v_fma_f32 v84, -v191, v86, v97
	v_cvt_pk_bf16_f32 v87, v85, v86
	v_fmac_f32_e32 v84, v190, v85
	v_fma_f32 v85, v191, v85, v101
	ds_write_b32 v205, v87 offset:12416
	v_fmac_f32_e32 v85, v190, v86
	v_fma_f32 v87, -v191, v85, v98
	v_fma_f32 v88, v191, v84, v102
	v_fmac_f32_e32 v88, v190, v85
	v_cvt_pk_bf16_f32 v86, v84, v85
	v_fmac_f32_e32 v87, v190, v84
	v_fma_f32 v96, -v191, v88, v99
	ds_write_b32 v205, v86 offset:12688
	v_mfma_f32_16x16x32_bf16 v[164:167], v[12:15], v[16:19], 0
	v_cvt_pk_bf16_f32 v84, v87, v88
	v_fmac_f32_e32 v96, v190, v87
	v_fmac_f32_e32 v103, v191, v87
	ds_write_b32 v205, v84 offset:12960
	v_fmac_f32_e32 v103, v190, v88
	v_mfma_f32_16x16x32_bf16 v[168:171], v[12:15], v[28:31], 0
	v_cvt_pk_bf16_f32 v84, v96, v103
	ds_write_b32 v205, v84 offset:13232
	ds_read_b128 v[84:87], v175 offset:48
	ds_read_b128 v[88:91], v175 offset:5168
	v_mfma_f32_16x16x32_bf16 v[64:67], v[12:15], v[32:35], 0
	s_waitcnt lgkmcnt(1)
	v_fma_f32 v84, -v191, v103, v84
	s_waitcnt lgkmcnt(0)
	v_fma_f32 v88, v191, v96, v88
	v_fmac_f32_e32 v84, v190, v96
	v_fmac_f32_e32 v88, v190, v103
	v_fma_f32 v85, -v191, v88, v85
	v_cvt_pk_bf16_f32 v96, v84, v88
	v_fmac_f32_e32 v85, v190, v84
	v_fma_f32 v84, v191, v84, v89
	ds_write_b32 v205, v96 offset:13504
	v_fmac_f32_e32 v84, v190, v88
	v_fma_f32 v86, -v191, v84, v86
	v_fma_f32 v89, v191, v85, v90
	v_cvt_pk_bf16_f32 v88, v85, v84
	v_fmac_f32_e32 v89, v190, v84
	ds_write_b32 v205, v88 offset:13776
	v_fmac_f32_e32 v86, v190, v85
	v_fma_f32 v88, -v191, v89, v87
	v_mfma_f32_16x16x32_bf16 v[68:71], v[12:15], v[36:39], 0
	v_cvt_pk_bf16_f32 v84, v86, v89
	v_fmac_f32_e32 v88, v190, v86
	v_fmac_f32_e32 v91, v191, v86
	ds_write_b32 v205, v84 offset:14048
	v_fmac_f32_e32 v91, v190, v89
	v_mfma_f32_16x16x32_bf16 v[72:75], v[12:15], v[40:43], 0
	v_cvt_pk_bf16_f32 v84, v88, v91
	ds_write_b32 v205, v84 offset:14320
	s_waitcnt lgkmcnt(0)
	ds_read_b128 v[84:87], v204 offset:10240
	ds_read_b128 v[96:99], v204 offset:10304
	ds_read_b128 v[100:103], v204 offset:10368
	ds_read_b128 v[104:107], v204 offset:10432
	s_waitcnt lgkmcnt(0)
	ds_write_b128 v201, v[128:131]
	ds_write_b128 v201, v[132:135] offset:1280
	ds_write_b128 v201, v[136:139] offset:2560
	ds_write_b128 v202, v[140:143]
	ds_write_b128 v201, v[144:147] offset:5120
	ds_write_b128 v201, v[148:151] offset:6400
	ds_write_b128 v201, v[152:155] offset:7680
	ds_write_b128 v203, v[156:159]
	s_waitcnt lgkmcnt(0)
	ds_read_b128 v[108:111], v175
	ds_read_b128 v[112:115], v175 offset:5120
	s_waitcnt lgkmcnt(13)
	v_mfma_f32_16x16x32_bf16 v[84:87], v[84:87], v[52:55], 0
	s_waitcnt lgkmcnt(1)
	v_fma_f32 v89, -v191, v91, v108
	s_waitcnt lgkmcnt(0)
	v_fma_f32 v90, v191, v88, v112
	v_fmac_f32_e32 v89, v190, v88
	v_fmac_f32_e32 v90, v190, v91
	v_fma_f32 v88, -v191, v90, v109
	v_cvt_pk_bf16_f32 v91, v89, v90
	v_fmac_f32_e32 v88, v190, v89
	v_fma_f32 v89, v191, v89, v113
	ds_write_b32 v205, v91 offset:10240
	v_fmac_f32_e32 v89, v190, v90
	v_fma_f32 v91, -v191, v89, v110
	v_fma_f32 v108, v191, v88, v114
	v_fmac_f32_e32 v108, v190, v89
	v_cvt_pk_bf16_f32 v90, v88, v89
	v_fmac_f32_e32 v91, v190, v88
	v_fma_f32 v112, -v191, v108, v111
	ds_write_b32 v205, v90 offset:10512
	v_mfma_f32_16x16x32_bf16 v[84:87], v[96:99], v[56:59], v[84:87]
	v_cvt_pk_bf16_f32 v88, v91, v108
	v_fmac_f32_e32 v112, v190, v91
	v_fmac_f32_e32 v115, v191, v91
	ds_write_b32 v205, v88 offset:10784
	v_fmac_f32_e32 v115, v190, v108
	v_mfma_f32_16x16x32_bf16 v[84:87], v[100:103], v[60:63], v[84:87]
	v_cvt_pk_bf16_f32 v88, v112, v115
	ds_write_b32 v205, v88 offset:11056
	ds_read_b128 v[88:91], v175 offset:16
	ds_read_b128 v[108:111], v175 offset:5136
	v_mfma_f32_16x16x32_bf16 v[76:79], v[12:15], v[44:47], 0
	s_waitcnt lgkmcnt(1)
	v_fma_f32 v88, -v191, v115, v88
	s_waitcnt lgkmcnt(0)
	v_fma_f32 v108, v191, v112, v108
	v_fmac_f32_e32 v88, v190, v112
	v_fmac_f32_e32 v108, v190, v115
	v_fma_f32 v89, -v191, v108, v89
	v_cvt_pk_bf16_f32 v112, v88, v108
	v_fmac_f32_e32 v89, v190, v88
	v_fma_f32 v88, v191, v88, v109
	ds_write_b32 v205, v112 offset:11328
	v_fmac_f32_e32 v88, v190, v108
	v_fma_f32 v90, -v191, v88, v90
	v_fma_f32 v109, v191, v89, v110
	v_cvt_pk_bf16_f32 v108, v89, v88
	v_fmac_f32_e32 v109, v190, v88
	ds_write_b32 v205, v108 offset:11600
	v_fmac_f32_e32 v90, v190, v89
	v_fma_f32 v108, -v191, v109, v91
	v_mfma_f32_16x16x32_bf16 v[80:83], v[12:15], v[48:51], 0
	v_cvt_pk_bf16_f32 v88, v90, v109
	v_fmac_f32_e32 v108, v190, v90
	v_fmac_f32_e32 v111, v191, v90
	ds_write_b32 v205, v88 offset:11872
	v_fmac_f32_e32 v111, v190, v109
	v_mfma_f32_16x16x32_bf16 v[24:27], v[206:209], v[60:63], v[24:27]
	v_cvt_pk_bf16_f32 v88, v108, v111
	ds_write_b32 v205, v88 offset:12144
	ds_read_b128 v[88:91], v175 offset:32
	ds_read_b128 v[112:115], v175 offset:5152
	v_mfma_f32_16x16x32_bf16 v[24:27], v[210:213], v[92:95], v[24:27]
	s_waitcnt lgkmcnt(1)
	v_fma_f32 v88, -v191, v111, v88
	s_waitcnt lgkmcnt(0)
	v_fma_f32 v96, v191, v108, v112
	v_fmac_f32_e32 v88, v190, v108
	v_fmac_f32_e32 v96, v190, v111
	v_fma_f32 v89, -v191, v96, v89
	v_cvt_pk_bf16_f32 v97, v88, v96
	v_fmac_f32_e32 v89, v190, v88
	v_fma_f32 v88, v191, v88, v113
	ds_write_b32 v205, v97 offset:12416
	v_fmac_f32_e32 v88, v190, v96
	v_fma_f32 v90, -v191, v88, v90
	v_fma_f32 v97, v191, v89, v114
	v_fmac_f32_e32 v97, v190, v88
	v_cvt_pk_bf16_f32 v96, v89, v88
	v_fmac_f32_e32 v90, v190, v89
	v_fma_f32 v108, -v191, v97, v91
	ds_write_b32 v205, v96 offset:12688
	s_nop 0
	v_cvt_pk_bf16_f32 v88, v90, v97
	v_fmac_f32_e32 v108, v190, v90
	v_fmac_f32_e32 v115, v191, v90
	ds_write_b32 v205, v88 offset:12960
	v_fmac_f32_e32 v115, v190, v97
	s_nop 0
	v_cvt_pk_bf16_f32 v88, v108, v115
	ds_write_b32 v205, v88 offset:13232
	ds_read_b128 v[88:91], v175 offset:48
	ds_read_b128 v[96:99], v175 offset:5168
	s_waitcnt lgkmcnt(1)
	v_fma_f32 v88, -v191, v115, v88
	s_waitcnt lgkmcnt(0)
	v_fma_f32 v96, v191, v108, v96
	v_fmac_f32_e32 v88, v190, v108
	v_fmac_f32_e32 v96, v190, v115
	v_fma_f32 v89, -v191, v96, v89
	v_cvt_pk_bf16_f32 v100, v88, v96
	v_fmac_f32_e32 v89, v190, v88
	v_fma_f32 v88, v191, v88, v97
	ds_write_b32 v205, v100 offset:13504
	v_fmac_f32_e32 v88, v190, v96
	v_fma_f32 v90, -v191, v88, v90
	v_fma_f32 v97, v191, v89, v98
	v_cvt_pk_bf16_f32 v96, v89, v88
	v_fmac_f32_e32 v97, v190, v88
	ds_write_b32 v205, v96 offset:13776
	v_fmac_f32_e32 v90, v190, v89
	v_fma_f32 v96, -v191, v97, v91
	s_nop 0
	v_cvt_pk_bf16_f32 v88, v90, v97
	v_fmac_f32_e32 v96, v190, v90
	v_fmac_f32_e32 v99, v191, v90
	ds_write_b32 v205, v88 offset:14048
	v_fmac_f32_e32 v99, v190, v97
	s_nop 0
	v_cvt_pk_bf16_f32 v88, v96, v99
	ds_write_b32 v205, v88 offset:14320
	s_waitcnt lgkmcnt(0)
	ds_read_b128 v[88:91], v204 offset:10240
	ds_read_b128 v[100:103], v204 offset:10304
	ds_read_b128 v[108:111], v204 offset:10368
	ds_read_b128 v[112:115], v204 offset:10432
	s_waitcnt lgkmcnt(0)
	ds_write_b128 v201, v[160:163]
	ds_write_b128 v201, v[164:167] offset:1280
	ds_write_b128 v201, v[168:171] offset:2560
	ds_write_b128 v202, v[64:67]
	ds_write_b128 v201, v[68:71] offset:5120
	ds_write_b128 v201, v[72:75] offset:6400
	ds_write_b128 v201, v[76:79] offset:7680
	ds_write_b128 v203, v[80:83]
	s_waitcnt lgkmcnt(0)
	ds_read_b128 v[16:19], v175
	ds_read_b128 v[28:31], v175 offset:5120
	s_waitcnt lgkmcnt(13)
	v_mfma_f32_16x16x32_bf16 v[36:39], v[88:91], v[52:55], 0
	s_waitcnt lgkmcnt(1)
	v_fma_f32 v16, -v191, v99, v16
	s_waitcnt lgkmcnt(0)
	v_fma_f32 v28, v191, v96, v28
	v_fmac_f32_e32 v16, v190, v96
	v_fmac_f32_e32 v28, v190, v99
	v_fma_f32 v17, -v191, v28, v17
	v_cvt_pk_bf16_f32 v32, v16, v28
	v_fmac_f32_e32 v17, v190, v16
	v_fma_f32 v16, v191, v16, v29
	ds_write_b32 v205, v32 offset:10240
	v_fmac_f32_e32 v16, v190, v28
	v_fma_f32 v18, -v191, v16, v18
	v_fma_f32 v29, v191, v17, v30
	v_cvt_pk_bf16_f32 v28, v17, v16
	v_fmac_f32_e32 v29, v190, v16
	ds_write_b32 v205, v28 offset:10512
	v_fmac_f32_e32 v18, v190, v17
	v_fma_f32 v28, -v191, v29, v19
	v_mfma_f32_16x16x32_bf16 v[36:39], v[100:103], v[56:59], v[36:39]
	v_cvt_pk_bf16_f32 v16, v18, v29
	v_fmac_f32_e32 v28, v190, v18
	v_fmac_f32_e32 v31, v191, v18
	ds_write_b32 v205, v16 offset:10784
	v_fmac_f32_e32 v31, v190, v29
	v_mfma_f32_16x16x32_bf16 v[36:39], v[108:111], v[60:63], v[36:39]
	v_cvt_pk_bf16_f32 v16, v28, v31
	ds_write_b32 v205, v16 offset:11056
	ds_read_b128 v[16:19], v175 offset:16
	ds_read_b128 v[32:35], v175 offset:5136
	v_mfma_f32_16x16x32_bf16 v[20:23], v[104:107], v[92:95], v[84:87]
	s_waitcnt lgkmcnt(1)
	v_fma_f32 v16, -v191, v31, v16
	s_waitcnt lgkmcnt(0)
	v_fma_f32 v29, v191, v28, v32
	v_fmac_f32_e32 v16, v190, v28
	v_fmac_f32_e32 v29, v190, v31
	v_fma_f32 v17, -v191, v29, v17
	v_cvt_pk_bf16_f32 v28, v16, v29
	v_fmac_f32_e32 v17, v190, v16
	v_fma_f32 v16, v191, v16, v33
	v_fmac_f32_e32 v16, v190, v29
	ds_write_b32 v205, v28 offset:11328
	v_fma_f32 v18, -v191, v16, v18
	v_cvt_pk_bf16_f32 v28, v17, v16
	v_fmac_f32_e32 v18, v190, v17
	v_fma_f32 v17, v191, v17, v34
	v_fmac_f32_e32 v17, v190, v16
	v_fma_f32 v32, -v191, v17, v19
	ds_write_b32 v205, v28 offset:11600
	s_nop 0
	v_cvt_pk_bf16_f32 v16, v18, v17
	v_fmac_f32_e32 v32, v190, v18
	v_fmac_f32_e32 v35, v191, v18
	ds_write_b32 v205, v16 offset:11872
	v_fmac_f32_e32 v35, v190, v17
	s_nop 0
	v_cvt_pk_bf16_f32 v16, v32, v35
	ds_write_b32 v205, v16 offset:12144
	ds_read_b128 v[16:19], v175 offset:32
	ds_read_b128 v[28:31], v175 offset:5152
	s_waitcnt lgkmcnt(1)
	v_fma_f32 v16, -v191, v35, v16
	s_waitcnt lgkmcnt(0)
	v_fma_f32 v28, v191, v32, v28
	v_fmac_f32_e32 v16, v190, v32
	v_fmac_f32_e32 v28, v190, v35
	v_fma_f32 v17, -v191, v28, v17
	v_cvt_pk_bf16_f32 v32, v16, v28
	v_fmac_f32_e32 v17, v190, v16
	v_fma_f32 v16, v191, v16, v29
	v_fmac_f32_e32 v16, v190, v28
	ds_write_b32 v205, v32 offset:12416
	v_fma_f32 v18, -v191, v16, v18
	v_cvt_pk_bf16_f32 v28, v17, v16
	v_fmac_f32_e32 v18, v190, v17
	v_fma_f32 v17, v191, v17, v30
	v_fmac_f32_e32 v17, v190, v16
	ds_write_b32 v205, v28 offset:12688
	v_fma_f32 v28, -v191, v17, v19
	s_nop 0
	v_cvt_pk_bf16_f32 v16, v18, v17
	v_fmac_f32_e32 v28, v190, v18
	v_fmac_f32_e32 v31, v191, v18
	ds_write_b32 v205, v16 offset:12960
	v_fmac_f32_e32 v31, v190, v17
	s_nop 0
	v_cvt_pk_bf16_f32 v16, v28, v31
	ds_write_b32 v205, v16 offset:13232
	ds_read_b128 v[16:19], v175 offset:48
	ds_read_b128 v[32:35], v175 offset:5168
	s_waitcnt lgkmcnt(1)
	v_fma_f32 v16, -v191, v31, v16
	v_fmac_f32_e32 v16, v190, v28
	s_waitcnt lgkmcnt(0)
	v_fma_f32 v28, v191, v28, v32
	v_fmac_f32_e32 v28, v190, v31
	v_fma_f32 v17, -v191, v28, v17
	v_cvt_pk_bf16_f32 v29, v16, v28
	v_fmac_f32_e32 v17, v190, v16
	v_fma_f32 v16, v191, v16, v33
	v_fmac_f32_e32 v16, v190, v28
	ds_write_b32 v205, v29 offset:13504
	v_fma_f32 v18, -v191, v16, v18
	v_cvt_pk_bf16_f32 v28, v17, v16
	v_fmac_f32_e32 v18, v190, v17
	v_fma_f32 v17, v191, v17, v34
	ds_write_b32 v205, v28 offset:13776
	v_fmac_f32_e32 v17, v190, v16
	v_mfma_f32_16x16x32_bf16 v[28:31], v[112:115], v[92:95], v[36:39]
	v_cvt_pk_bf16_f32 v16, v18, v17
	ds_write_b32 v205, v16 offset:14048
	v_fma_f32 v16, -v191, v17, v19
	v_fmac_f32_e32 v16, v190, v18
	v_fmac_f32_e32 v35, v191, v18
	v_fmac_f32_e32 v35, v190, v17
	v_cvt_pk_bf16_f32 v16, v16, v35
	ds_write_b32 v205, v16 offset:14320
	s_waitcnt lgkmcnt(0)
	ds_read_b128 v[16:19], v204 offset:10240
	ds_read_b128 v[32:35], v204 offset:10304
	s_waitcnt lgkmcnt(1)
	v_mfma_f32_16x16x32_bf16 v[16:19], v[16:19], v[52:55], 0
	s_waitcnt lgkmcnt(0)
	v_mfma_f32_16x16x32_bf16 v[16:19], v[32:35], v[56:59], v[16:19]
	ds_read_b128 v[32:35], v204 offset:10368
	ds_read_b128 v[36:39], v204 offset:10432
	s_waitcnt lgkmcnt(0)
	s_waitcnt lgkmcnt(1)
	v_mfma_f32_16x16x32_bf16 v[16:19], v[32:35], v[60:63], v[16:19]
	v_lshl_or_b32 v32, s10, 9, v182
	global_load_dwordx2 v[168:169], v32, s[92:93]
	v_mov_b32_e32 v32, 0
	s_waitcnt lgkmcnt(0)
	v_mfma_f32_16x16x32_bf16 v[16:19], v[36:39], v[92:95], v[16:19]
	v_mov_b32_e32 v33, 0
	v_mov_b32_e32 v34, 0
	v_mov_b32_e32 v36, 0
	v_mov_b32_e32 v35, 0
	s_and_saveexec_b64 s[4:5], vcc
	s_cbranch_execz .LBB0_1548
	v_lshl_add_u64 v[32:33], v[180:181], 0, v[176:177]
	global_load_dwordx4 v[32:35], v[32:33], off
